# v55 + P8 first merge epilogue: all 16 gate loads issued up front into dead registers (was 1 group ahead), waits recounted
# speedup vs baseline: 1.0006x; 1.0006x over previous
.LBB0_845:
	v_lshl_add_u32 v144, s41, 8, v152
	v_lshl_add_u32 v146, s40, 8, v150
	v_ashrrev_i32_e32 v145, 31, v144
	v_mov_b64_e32 v[148:149], s[12:13]
	v_mad_i64_i32 v[156:157], s[0:1], v146, s38, v[148:149]
	v_lshlrev_b64 v[144:145], 1, v[144:145]
	v_lshl_add_u64 v[160:161], v[156:157], 0, v[144:145]
	v_mov_b32_e32 v172, v160
	v_mov_b32_e32 v173, v161
	s_mov_b32 s6, 0x4e000
	s_mov_b32 s7, 0
	s_mov_b32 s44, 0x186000
	s_mov_b32 s45, 0
	global_load_dwordx4 v[174:177], v[172:173], off
	global_load_dwordx4 v[178:181], v[172:173], off offset:256
	v_lshl_add_u64 v[172:173], v[172:173], 0, s[6:7]
	global_load_dwordx4 v[184:187], v[172:173], off
	global_load_dwordx4 v[188:191], v[172:173], off offset:256
	v_lshl_add_u64 v[172:173], v[172:173], 0, s[6:7]
	global_load_dwordx4 v[192:195], v[172:173], off
	global_load_dwordx4 v[196:199], v[172:173], off offset:256
	v_lshl_add_u64 v[172:173], v[172:173], 0, s[6:7]
	global_load_dwordx4 v[200:203], v[172:173], off
	global_load_dwordx4 v[204:207], v[172:173], off offset:256
	v_lshl_add_u64 v[172:173], v[172:173], 0, s[44:45]
	global_load_dwordx4 v[208:211], v[172:173], off
	global_load_dwordx4 v[212:215], v[172:173], off offset:256
	v_lshl_add_u64 v[172:173], v[172:173], 0, s[6:7]
	global_load_dwordx4 v[216:219], v[172:173], off
	global_load_dwordx4 v[220:223], v[172:173], off offset:256
	v_lshl_add_u64 v[172:173], v[172:173], 0, s[6:7]
	global_load_dwordx4 v[224:227], v[172:173], off
	global_load_dwordx4 v[228:231], v[172:173], off offset:256
	v_lshl_add_u64 v[172:173], v[172:173], 0, s[6:7]
	global_load_dwordx4 v[236:239], v[172:173], off
	global_load_dwordx4 v[240:243], v[172:173], off offset:256
	v_ashrrev_i32_e32 v147, 31, v146
	v_readlane_b32 s2, v235, 19
	v_lshlrev_b64 v[162:163], 12, v[146:147]
	v_readlane_b32 s3, v235, 20
	v_or_b32_e32 v164, 16, v146
	v_mad_i64_i32 v[166:167], s[0:1], v164, s38, v[148:149]
	v_lshl_add_u64 v[162:163], s[2:3], 0, v[162:163]
	v_lshl_add_u64 v[168:169], v[162:163], 0, v[144:145]
	v_lshl_add_u64 v[166:167], v[166:167], 0, v[144:145]
	s_and_b64 vcc, exec, s[4:5]
	s_waitcnt vmcnt(14)
	v_lshlrev_b32_e32 v171, 16, v177
	v_and_b32_e32 v159, 0xffff0000, v177
	v_lshlrev_b32_e32 v147, 16, v174
	v_and_b32_e32 v156, 0xffff0000, v174
	v_lshlrev_b32_e32 v165, 16, v175
	v_and_b32_e32 v157, 0xffff0000, v175
	v_lshlrev_b32_e32 v170, 16, v176
	v_and_b32_e32 v158, 0xffff0000, v176
	v_mul_f32_e32 v159, 0xbfb8aa3b, v159
	v_mul_f32_e32 v147, 0xbfb8aa3b, v147
	v_mul_f32_e32 v156, 0xbfb8aa3b, v156
	v_mul_f32_e32 v165, 0xbfb8aa3b, v165
	v_mul_f32_e32 v157, 0xbfb8aa3b, v157
	v_mul_f32_e32 v170, 0xbfb8aa3b, v170
	v_mul_f32_e32 v158, 0xbfb8aa3b, v158
	v_mul_f32_e32 v171, 0xbfb8aa3b, v171
	v_exp_f32_e32 v159, v159
	v_exp_f32_e32 v147, v147
	v_exp_f32_e32 v156, v156
	v_exp_f32_e32 v165, v165
	v_exp_f32_e32 v157, v157
	v_exp_f32_e32 v170, v170
	v_exp_f32_e32 v158, v158
	v_exp_f32_e32 v171, v171
	v_add_f32_e32 v159, 1.0, v159
	v_add_f32_e32 v147, 1.0, v147
	v_add_f32_e32 v156, 1.0, v156
	v_add_f32_e32 v165, 1.0, v165
	v_add_f32_e32 v157, 1.0, v157
	v_add_f32_e32 v170, 1.0, v170
	v_add_f32_e32 v158, 1.0, v158
	v_add_f32_e32 v171, 1.0, v171
	v_rcp_f32_e32 v159, v159
	v_rcp_f32_e32 v147, v147
	v_rcp_f32_e32 v156, v156
	v_rcp_f32_e32 v165, v165
	v_rcp_f32_e32 v157, v157
	v_rcp_f32_e32 v170, v170
	v_rcp_f32_e32 v158, v158
	v_rcp_f32_e32 v171, v171
	v_mul_f32_e32 v123, v123, v159
	v_mul_f32_e32 v124, v124, v147
	v_mul_f32_e32 v125, v125, v156
	v_mul_f32_e32 v126, v126, v165
	v_mul_f32_e32 v127, v127, v157
	v_mul_f32_e32 v147, v120, v170
	v_mul_f32_e32 v156, v121, v158
	v_mul_f32_e32 v157, v122, v171
	v_cvt_pk_bf16_f32 v120, v124, v125
	v_cvt_pk_bf16_f32 v121, v126, v127
	v_cvt_pk_bf16_f32 v122, v147, v156
	v_cvt_pk_bf16_f32 v123, v157, v123
	global_store_dwordx4 v[168:169], v[120:123], off
	v_lshlrev_b32_e32 v125, 16, v178
	v_and_b32_e32 v147, 0xffff0000, v178
	v_lshlrev_b32_e32 v158, 16, v179
	v_and_b32_e32 v159, 0xffff0000, v179
	v_lshlrev_b32_e32 v160, 16, v180
	v_and_b32_e32 v161, 0xffff0000, v180
	v_lshlrev_b32_e32 v162, 16, v181
	v_and_b32_e32 v163, 0xffff0000, v181
	v_mul_f32_e32 v163, 0xbfb8aa3b, v163
	v_mul_f32_e32 v125, 0xbfb8aa3b, v125
	v_mul_f32_e32 v147, 0xbfb8aa3b, v147
	v_mul_f32_e32 v158, 0xbfb8aa3b, v158
	v_mul_f32_e32 v159, 0xbfb8aa3b, v159
	v_mul_f32_e32 v160, 0xbfb8aa3b, v160
	v_mul_f32_e32 v161, 0xbfb8aa3b, v161
	v_mul_f32_e32 v162, 0xbfb8aa3b, v162
	v_exp_f32_e32 v163, v163
	v_exp_f32_e32 v125, v125
	v_exp_f32_e32 v147, v147
	v_exp_f32_e32 v158, v158
	v_exp_f32_e32 v159, v159
	v_exp_f32_e32 v160, v160
	v_exp_f32_e32 v161, v161
	v_exp_f32_e32 v162, v162
	v_add_f32_e32 v163, 1.0, v163
	v_add_f32_e32 v125, 1.0, v125
	v_add_f32_e32 v147, 1.0, v147
	v_add_f32_e32 v158, 1.0, v158
	v_add_f32_e32 v159, 1.0, v159
	v_add_f32_e32 v160, 1.0, v160
	v_add_f32_e32 v161, 1.0, v161
	v_add_f32_e32 v162, 1.0, v162
	v_rcp_f32_e32 v163, v163
	v_rcp_f32_e32 v125, v125
	v_rcp_f32_e32 v147, v147
	v_rcp_f32_e32 v158, v158
	v_rcp_f32_e32 v159, v159
	v_rcp_f32_e32 v160, v160
	v_rcp_f32_e32 v161, v161
	v_rcp_f32_e32 v162, v162
	v_mul_f32_e32 v115, v115, v163
	v_mul_f32_e32 v116, v116, v125
	v_mul_f32_e32 v117, v117, v147
	v_mul_f32_e32 v118, v118, v158
	v_mul_f32_e32 v119, v119, v159
	v_mul_f32_e32 v125, v112, v160
	v_mul_f32_e32 v147, v113, v161
	v_mul_f32_e32 v158, v114, v162
	v_cvt_pk_bf16_f32 v112, v116, v117
	v_cvt_pk_bf16_f32 v113, v118, v119
	v_cvt_pk_bf16_f32 v114, v125, v147
	v_cvt_pk_bf16_f32 v115, v158, v115
	global_store_dwordx4 v[168:169], v[112:115], off offset:256
	v_ashrrev_i32_e32 v165, 31, v164
	v_lshlrev_b64 v[156:157], 12, v[164:165]
	v_or_b32_e32 v124, 32, v146
	v_lshl_add_u64 v[156:157], s[2:3], 0, v[156:157]
	v_mad_i64_i32 v[126:127], s[0:1], v124, s38, v[148:149]
	v_lshl_add_u64 v[156:157], v[156:157], 0, v[144:145]
	v_lshl_add_u64 v[126:127], v[126:127], 0, v[144:145]
	v_ashrrev_i32_e32 v125, 31, v124
	s_waitcnt vmcnt(15)
	v_lshlrev_b32_e32 v116, 16, v184
	v_and_b32_e32 v117, 0xffff0000, v184
	v_lshlrev_b32_e32 v118, 16, v185
	v_and_b32_e32 v119, 0xffff0000, v185
	v_lshlrev_b32_e32 v120, 16, v186
	v_and_b32_e32 v121, 0xffff0000, v186
	v_lshlrev_b32_e32 v122, 16, v187
	v_and_b32_e32 v123, 0xffff0000, v187
	v_mul_f32_e32 v123, 0xbfb8aa3b, v123
	v_mul_f32_e32 v116, 0xbfb8aa3b, v116
	v_mul_f32_e32 v117, 0xbfb8aa3b, v117
	v_mul_f32_e32 v118, 0xbfb8aa3b, v118
	v_mul_f32_e32 v119, 0xbfb8aa3b, v119
	v_mul_f32_e32 v120, 0xbfb8aa3b, v120
	v_mul_f32_e32 v121, 0xbfb8aa3b, v121
	v_mul_f32_e32 v122, 0xbfb8aa3b, v122
	v_exp_f32_e32 v123, v123
	v_exp_f32_e32 v116, v116
	v_exp_f32_e32 v117, v117
	v_exp_f32_e32 v118, v118
	v_exp_f32_e32 v119, v119
	v_exp_f32_e32 v120, v120
	v_exp_f32_e32 v121, v121
	v_exp_f32_e32 v122, v122
	v_add_f32_e32 v123, 1.0, v123
	v_add_f32_e32 v116, 1.0, v116
	v_add_f32_e32 v117, 1.0, v117
	v_add_f32_e32 v118, 1.0, v118
	v_add_f32_e32 v119, 1.0, v119
	v_add_f32_e32 v120, 1.0, v120
	v_add_f32_e32 v121, 1.0, v121
	v_add_f32_e32 v122, 1.0, v122
	v_rcp_f32_e32 v123, v123
	v_rcp_f32_e32 v116, v116
	v_rcp_f32_e32 v117, v117
	v_rcp_f32_e32 v118, v118
	v_rcp_f32_e32 v119, v119
	v_rcp_f32_e32 v120, v120
	v_rcp_f32_e32 v121, v121
	v_rcp_f32_e32 v122, v122
	v_mul_f32_e32 v107, v107, v123
	v_mul_f32_e32 v108, v108, v116
	v_mul_f32_e32 v109, v109, v117
	v_mul_f32_e32 v110, v110, v118
	v_mul_f32_e32 v111, v111, v119
	v_mul_f32_e32 v116, v104, v120
	v_mul_f32_e32 v117, v105, v121
	v_mul_f32_e32 v118, v106, v122
	v_cvt_pk_bf16_f32 v104, v108, v109
	v_cvt_pk_bf16_f32 v105, v110, v111
	v_cvt_pk_bf16_f32 v106, v116, v117
	v_cvt_pk_bf16_f32 v107, v118, v107
	global_store_dwordx4 v[156:157], v[104:107], off
	s_waitcnt vmcnt(15)
	v_lshlrev_b32_e32 v117, 16, v191
	v_and_b32_e32 v115, 0xffff0000, v191
	v_lshlrev_b32_e32 v110, 16, v188
	v_and_b32_e32 v111, 0xffff0000, v188
	v_lshlrev_b32_e32 v112, 16, v189
	v_and_b32_e32 v113, 0xffff0000, v189
	v_lshlrev_b32_e32 v116, 16, v190
	v_and_b32_e32 v114, 0xffff0000, v190
	v_mul_f32_e32 v115, 0xbfb8aa3b, v115
	v_mul_f32_e32 v110, 0xbfb8aa3b, v110
	v_mul_f32_e32 v111, 0xbfb8aa3b, v111
	v_mul_f32_e32 v112, 0xbfb8aa3b, v112
	v_mul_f32_e32 v113, 0xbfb8aa3b, v113
	v_mul_f32_e32 v116, 0xbfb8aa3b, v116
	v_mul_f32_e32 v114, 0xbfb8aa3b, v114
	v_mul_f32_e32 v117, 0xbfb8aa3b, v117
	v_exp_f32_e32 v115, v115
	v_exp_f32_e32 v110, v110
	v_exp_f32_e32 v111, v111
	v_exp_f32_e32 v112, v112
	v_exp_f32_e32 v113, v113
	v_exp_f32_e32 v116, v116
	v_exp_f32_e32 v114, v114
	v_exp_f32_e32 v117, v117
	v_add_f32_e32 v115, 1.0, v115
	v_add_f32_e32 v110, 1.0, v110
	v_add_f32_e32 v111, 1.0, v111
	v_add_f32_e32 v112, 1.0, v112
	v_add_f32_e32 v113, 1.0, v113
	v_add_f32_e32 v116, 1.0, v116
	v_add_f32_e32 v114, 1.0, v114
	v_add_f32_e32 v117, 1.0, v117
	v_rcp_f32_e32 v115, v115
	v_rcp_f32_e32 v110, v110
	v_rcp_f32_e32 v111, v111
	v_rcp_f32_e32 v112, v112
	v_rcp_f32_e32 v113, v113
	v_rcp_f32_e32 v116, v116
	v_rcp_f32_e32 v114, v114
	v_rcp_f32_e32 v117, v117
	v_mul_f32_e32 v99, v99, v115
	v_mul_f32_e32 v100, v100, v110
	v_mul_f32_e32 v101, v101, v111
	v_mul_f32_e32 v102, v102, v112
	v_mul_f32_e32 v103, v103, v113
	v_mul_f32_e32 v110, v96, v116
	v_mul_f32_e32 v111, v97, v114
	v_mul_f32_e32 v112, v98, v117
	v_cvt_pk_bf16_f32 v96, v100, v101
	v_cvt_pk_bf16_f32 v97, v102, v103
	v_cvt_pk_bf16_f32 v98, v110, v111
	v_cvt_pk_bf16_f32 v99, v112, v99
	global_store_dwordx4 v[156:157], v[96:99], off offset:256
	v_lshlrev_b64 v[108:109], 12, v[124:125]
	s_waitcnt vmcnt(15)
	v_lshlrev_b32_e32 v100, 16, v192
	v_and_b32_e32 v101, 0xffff0000, v192
	v_mul_f32_e32 v100, 0xbfb8aa3b, v100
	v_mul_f32_e32 v101, 0xbfb8aa3b, v101
	v_exp_f32_e32 v100, v100
	v_exp_f32_e32 v101, v101
	v_lshlrev_b32_e32 v102, 16, v193
	v_and_b32_e32 v103, 0xffff0000, v193
	v_lshlrev_b32_e32 v104, 16, v194
	v_and_b32_e32 v105, 0xffff0000, v194
	v_lshlrev_b32_e32 v106, 16, v195
	v_and_b32_e32 v107, 0xffff0000, v195
	v_mul_f32_e32 v102, 0xbfb8aa3b, v102
	v_mul_f32_e32 v103, 0xbfb8aa3b, v103
	v_mul_f32_e32 v104, 0xbfb8aa3b, v104
	v_mul_f32_e32 v105, 0xbfb8aa3b, v105
	v_mul_f32_e32 v106, 0xbfb8aa3b, v106
	v_mul_f32_e32 v107, 0xbfb8aa3b, v107
	v_exp_f32_e32 v102, v102
	v_exp_f32_e32 v103, v103
	v_exp_f32_e32 v104, v104
	v_exp_f32_e32 v105, v105
	v_add_f32_e32 v100, 1.0, v100
	v_add_f32_e32 v101, 1.0, v101
	v_exp_f32_e32 v106, v106
	v_exp_f32_e32 v107, v107
	v_rcp_f32_e32 v100, v100
	v_rcp_f32_e32 v101, v101
	v_add_f32_e32 v102, 1.0, v102
	v_add_f32_e32 v103, 1.0, v103
	v_add_f32_e32 v104, 1.0, v104
	v_add_f32_e32 v105, 1.0, v105
	v_rcp_f32_e32 v102, v102
	v_rcp_f32_e32 v103, v103
	v_rcp_f32_e32 v104, v104
	v_rcp_f32_e32 v105, v105
	v_mul_f32_e32 v100, v92, v100
	v_mul_f32_e32 v101, v93, v101
	v_add_f32_e32 v92, 1.0, v106
	v_add_f32_e32 v93, 1.0, v107
	v_rcp_f32_e32 v92, v92
	v_rcp_f32_e32 v93, v93
	v_mul_f32_e32 v94, v94, v102
	v_mul_f32_e32 v95, v95, v103
	v_mul_f32_e32 v102, v88, v104
	v_mul_f32_e32 v103, v89, v105
	v_lshl_add_u64 v[88:89], s[2:3], 0, v[108:109]
	v_mul_f32_e32 v104, v90, v92
	v_mul_f32_e32 v91, v91, v93
	v_lshl_add_u64 v[92:93], v[88:89], 0, v[144:145]
	v_cvt_pk_bf16_f32 v88, v100, v101
	v_cvt_pk_bf16_f32 v89, v94, v95
	v_or_b32_e32 v94, 48, v146
	v_cvt_pk_bf16_f32 v90, v102, v103
	v_cvt_pk_bf16_f32 v91, v104, v91
	global_store_dwordx4 v[92:93], v[88:91], off
	s_waitcnt vmcnt(15)
	v_lshlrev_b32_e32 v104, 16, v199
	v_and_b32_e32 v99, 0xffff0000, v199
	v_mad_i64_i32 v[88:89], s[0:1], v94, s38, v[148:149]
	v_lshl_add_u64 v[100:101], v[88:89], 0, v[144:145]
	v_lshlrev_b32_e32 v95, 16, v196
	v_and_b32_e32 v96, 0xffff0000, v196
	v_lshlrev_b32_e32 v102, 16, v197
	v_and_b32_e32 v97, 0xffff0000, v197
	v_lshlrev_b32_e32 v103, 16, v198
	v_and_b32_e32 v98, 0xffff0000, v198
	v_mul_f32_e32 v99, 0xbfb8aa3b, v99
	v_mul_f32_e32 v95, 0xbfb8aa3b, v95
	v_mul_f32_e32 v96, 0xbfb8aa3b, v96
	v_mul_f32_e32 v102, 0xbfb8aa3b, v102
	v_mul_f32_e32 v97, 0xbfb8aa3b, v97
	v_mul_f32_e32 v103, 0xbfb8aa3b, v103
	v_mul_f32_e32 v98, 0xbfb8aa3b, v98
	v_mul_f32_e32 v104, 0xbfb8aa3b, v104
	v_exp_f32_e32 v99, v99
	v_exp_f32_e32 v95, v95
	v_exp_f32_e32 v96, v96
	v_exp_f32_e32 v102, v102
	v_exp_f32_e32 v97, v97
	v_exp_f32_e32 v103, v103
	v_exp_f32_e32 v98, v98
	v_exp_f32_e32 v104, v104
	v_add_f32_e32 v99, 1.0, v99
	v_add_f32_e32 v95, 1.0, v95
	v_add_f32_e32 v96, 1.0, v96
	v_add_f32_e32 v102, 1.0, v102
	v_add_f32_e32 v97, 1.0, v97
	v_add_f32_e32 v103, 1.0, v103
	v_add_f32_e32 v98, 1.0, v98
	v_add_f32_e32 v104, 1.0, v104
	v_rcp_f32_e32 v99, v99
	v_rcp_f32_e32 v95, v95
	v_rcp_f32_e32 v96, v96
	v_rcp_f32_e32 v102, v102
	v_rcp_f32_e32 v97, v97
	v_rcp_f32_e32 v103, v103
	v_rcp_f32_e32 v98, v98
	v_rcp_f32_e32 v104, v104
	v_mul_f32_e32 v83, v83, v99
	v_mul_f32_e32 v84, v84, v95
	v_mul_f32_e32 v85, v85, v96
	v_mul_f32_e32 v86, v86, v102
	v_mul_f32_e32 v87, v87, v97
	v_mul_f32_e32 v95, v80, v103
	v_mul_f32_e32 v96, v81, v98
	v_mul_f32_e32 v97, v82, v104
	v_cvt_pk_bf16_f32 v80, v84, v85
	v_cvt_pk_bf16_f32 v81, v86, v87
	v_cvt_pk_bf16_f32 v82, v95, v96
	v_cvt_pk_bf16_f32 v83, v97, v83
	global_store_dwordx4 v[92:93], v[80:83], off offset:256
	v_ashrrev_i32_e32 v95, 31, v94
	s_waitcnt vmcnt(15)
	v_and_b32_e32 v85, 0xffff0000, v200
	v_lshlrev_b32_e32 v86, 16, v201
	v_lshlrev_b32_e32 v84, 16, v200
	v_mul_f32_e32 v85, 0xbfb8aa3b, v85
	v_mul_f32_e32 v86, 0xbfb8aa3b, v86
	v_mul_f32_e32 v84, 0xbfb8aa3b, v84
	v_exp_f32_e32 v88, v85
	v_exp_f32_e32 v86, v86
	v_exp_f32_e32 v87, v84
	v_and_b32_e32 v89, 0xffff0000, v201
	v_add_f32_e32 v88, 1.0, v88
	v_add_f32_e32 v86, 1.0, v86
	v_add_f32_e32 v87, 1.0, v87
	v_rcp_f32_e32 v88, v88
	v_rcp_f32_e32 v86, v86
	v_mul_f32_e32 v89, 0xbfb8aa3b, v89
	v_rcp_f32_e32 v87, v87
	v_exp_f32_e32 v89, v89
	v_mul_f32_e32 v88, v77, v88
	v_mul_f32_e32 v78, v78, v86
	v_lshlrev_b32_e32 v77, 16, v202
	v_and_b32_e32 v86, 0xffff0000, v202
	v_mul_f32_e32 v87, v76, v87
	v_add_f32_e32 v76, 1.0, v89
	v_mul_f32_e32 v77, 0xbfb8aa3b, v77
	v_mul_f32_e32 v86, 0xbfb8aa3b, v86
	v_rcp_f32_e32 v76, v76
	v_exp_f32_e32 v77, v77
	v_exp_f32_e32 v86, v86
	v_and_b32_e32 v89, 0xffff0000, v203
	v_mul_f32_e32 v79, v79, v76
	v_add_f32_e32 v76, 1.0, v77
	v_add_f32_e32 v77, 1.0, v86
	v_lshlrev_b32_e32 v86, 16, v203
	v_mul_f32_e32 v89, 0xbfb8aa3b, v89
	v_mul_f32_e32 v86, 0xbfb8aa3b, v86
	v_exp_f32_e32 v89, v89
	v_exp_f32_e32 v86, v86
	v_rcp_f32_e32 v76, v76
	v_rcp_f32_e32 v77, v77
	v_add_f32_e32 v89, 1.0, v89
	v_add_f32_e32 v86, 1.0, v86
	v_rcp_f32_e32 v89, v89
	v_rcp_f32_e32 v86, v86
	v_lshlrev_b64 v[84:85], 12, v[94:95]
	v_mul_f32_e32 v90, v72, v76
	v_mul_f32_e32 v91, v73, v77
	v_lshl_add_u64 v[72:73], s[2:3], 0, v[84:85]
	v_mul_f32_e32 v75, v75, v89
	v_lshl_add_u64 v[76:77], v[72:73], 0, v[144:145]
	v_cvt_pk_bf16_f32 v72, v87, v88
	v_cvt_pk_bf16_f32 v73, v78, v79
	v_add_u32_e32 v78, 0x80, v146
	v_mul_f32_e32 v86, v74, v86
	v_cvt_pk_bf16_f32 v74, v90, v91
	v_cvt_pk_bf16_f32 v75, v86, v75
	global_store_dwordx4 v[76:77], v[72:75], off
	s_waitcnt vmcnt(15)
	v_lshlrev_b32_e32 v79, 16, v204
	v_and_b32_e32 v80, 0xffff0000, v204
	v_mad_i64_i32 v[72:73], s[0:1], v78, s38, v[148:149]
	v_lshl_add_u64 v[84:85], v[72:73], 0, v[144:145]
	v_mul_f32_e32 v79, 0xbfb8aa3b, v79
	v_mul_f32_e32 v80, 0xbfb8aa3b, v80
	v_exp_f32_e32 v79, v79
	v_exp_f32_e32 v80, v80
	v_lshlrev_b32_e32 v86, 16, v205
	v_and_b32_e32 v81, 0xffff0000, v205
	v_add_f32_e32 v79, 1.0, v79
	v_add_f32_e32 v80, 1.0, v80
	v_mul_f32_e32 v81, 0xbfb8aa3b, v81
	v_rcp_f32_e32 v79, v79
	v_rcp_f32_e32 v80, v80
	v_exp_f32_e32 v81, v81
	v_mul_f32_e32 v86, 0xbfb8aa3b, v86
	v_mul_f32_e32 v68, v68, v79
	v_mul_f32_e32 v69, v69, v80
	v_add_f32_e32 v79, 1.0, v81
	v_lshlrev_b32_e32 v80, 16, v206
	v_and_b32_e32 v81, 0xffff0000, v206
	v_mul_f32_e32 v80, 0xbfb8aa3b, v80
	v_mul_f32_e32 v81, 0xbfb8aa3b, v81
	v_rcp_f32_e32 v79, v79
	v_exp_f32_e32 v80, v80
	v_exp_f32_e32 v81, v81
	v_and_b32_e32 v82, 0xffff0000, v207
	v_mul_f32_e32 v71, v71, v79
	v_add_f32_e32 v79, 1.0, v80
	v_add_f32_e32 v80, 1.0, v81
	v_lshlrev_b32_e32 v81, 16, v207
	v_mul_f32_e32 v82, 0xbfb8aa3b, v82
	v_mul_f32_e32 v81, 0xbfb8aa3b, v81
	v_exp_f32_e32 v82, v82
	v_exp_f32_e32 v86, v86
	v_exp_f32_e32 v81, v81
	v_rcp_f32_e32 v79, v79
	v_add_f32_e32 v82, 1.0, v82
	v_add_f32_e32 v86, 1.0, v86
	v_add_f32_e32 v81, 1.0, v81
	v_rcp_f32_e32 v82, v82
	v_rcp_f32_e32 v86, v86
	v_rcp_f32_e32 v80, v80
	v_rcp_f32_e32 v81, v81
	v_mul_f32_e32 v67, v67, v82
	v_mul_f32_e32 v70, v70, v86
	v_mul_f32_e32 v79, v64, v79
	v_mul_f32_e32 v80, v65, v80
	v_mul_f32_e32 v81, v66, v81
	v_cvt_pk_bf16_f32 v64, v68, v69
	v_cvt_pk_bf16_f32 v65, v70, v71
	v_cvt_pk_bf16_f32 v66, v79, v80
	v_cvt_pk_bf16_f32 v67, v81, v67
	global_store_dwordx4 v[76:77], v[64:67], off offset:256
	v_ashrrev_i32_e32 v79, 31, v78
	s_waitcnt vmcnt(15)
	v_lshlrev_b32_e32 v68, 16, v208
	v_and_b32_e32 v71, 0xffff0000, v208
	v_lshlrev_b32_e32 v72, 16, v209
	v_mul_f32_e32 v71, 0xbfb8aa3b, v71
	v_mul_f32_e32 v72, 0xbfb8aa3b, v72
	v_mul_f32_e32 v68, 0xbfb8aa3b, v68
	v_exp_f32_e32 v71, v71
	v_exp_f32_e32 v72, v72
	v_exp_f32_e32 v70, v68
	v_and_b32_e32 v73, 0xffff0000, v209
	v_add_f32_e32 v71, 1.0, v71
	v_add_f32_e32 v72, 1.0, v72
	v_add_f32_e32 v70, 1.0, v70
	v_rcp_f32_e32 v71, v71
	v_rcp_f32_e32 v72, v72
	v_mul_f32_e32 v73, 0xbfb8aa3b, v73
	v_rcp_f32_e32 v70, v70
	v_exp_f32_e32 v73, v73
	v_mul_f32_e32 v71, v61, v71
	v_mul_f32_e32 v62, v62, v72
	v_lshlrev_b32_e32 v61, 16, v210
	v_and_b32_e32 v72, 0xffff0000, v210
	v_mul_f32_e32 v70, v60, v70
	v_add_f32_e32 v60, 1.0, v73
	v_mul_f32_e32 v61, 0xbfb8aa3b, v61
	v_mul_f32_e32 v72, 0xbfb8aa3b, v72
	v_rcp_f32_e32 v60, v60
	v_exp_f32_e32 v61, v61
	v_exp_f32_e32 v72, v72
	v_and_b32_e32 v73, 0xffff0000, v211
	v_mul_f32_e32 v63, v63, v60
	v_add_f32_e32 v60, 1.0, v61
	v_add_f32_e32 v61, 1.0, v72
	v_lshlrev_b32_e32 v72, 16, v211
	v_mul_f32_e32 v73, 0xbfb8aa3b, v73
	v_mul_f32_e32 v72, 0xbfb8aa3b, v72
	v_exp_f32_e32 v73, v73
	v_exp_f32_e32 v72, v72
	v_rcp_f32_e32 v60, v60
	v_rcp_f32_e32 v61, v61
	v_add_f32_e32 v73, 1.0, v73
	v_add_f32_e32 v72, 1.0, v72
	v_rcp_f32_e32 v73, v73
	v_rcp_f32_e32 v72, v72
	v_lshlrev_b64 v[68:69], 12, v[78:79]
	v_mul_f32_e32 v74, v56, v60
	v_mul_f32_e32 v75, v57, v61
	v_lshl_add_u64 v[56:57], s[2:3], 0, v[68:69]
	v_mul_f32_e32 v59, v59, v73
	v_lshl_add_u64 v[60:61], v[56:57], 0, v[144:145]
	v_cvt_pk_bf16_f32 v56, v70, v71
	v_cvt_pk_bf16_f32 v57, v62, v63
	v_add_u32_e32 v62, 0x90, v146
	v_mul_f32_e32 v72, v58, v72
	v_cvt_pk_bf16_f32 v58, v74, v75
	v_cvt_pk_bf16_f32 v59, v72, v59
	global_store_dwordx4 v[60:61], v[56:59], off
	s_waitcnt vmcnt(15)
	v_lshlrev_b32_e32 v63, 16, v212
	v_and_b32_e32 v64, 0xffff0000, v212
	v_mad_i64_i32 v[56:57], s[0:1], v62, s38, v[148:149]
	v_lshl_add_u64 v[68:69], v[56:57], 0, v[144:145]
	v_mul_f32_e32 v63, 0xbfb8aa3b, v63
	v_mul_f32_e32 v64, 0xbfb8aa3b, v64
	v_exp_f32_e32 v63, v63
	v_exp_f32_e32 v64, v64
	v_lshlrev_b32_e32 v70, 16, v213
	v_and_b32_e32 v65, 0xffff0000, v213
	v_add_f32_e32 v63, 1.0, v63
	v_add_f32_e32 v64, 1.0, v64
	v_mul_f32_e32 v65, 0xbfb8aa3b, v65
	v_rcp_f32_e32 v63, v63
	v_rcp_f32_e32 v64, v64
	v_exp_f32_e32 v65, v65
	v_mul_f32_e32 v70, 0xbfb8aa3b, v70
	v_mul_f32_e32 v52, v52, v63
	v_mul_f32_e32 v53, v53, v64
	v_add_f32_e32 v63, 1.0, v65
	v_lshlrev_b32_e32 v64, 16, v214
	v_and_b32_e32 v65, 0xffff0000, v214
	v_mul_f32_e32 v64, 0xbfb8aa3b, v64
	v_mul_f32_e32 v65, 0xbfb8aa3b, v65
	v_rcp_f32_e32 v63, v63
	v_exp_f32_e32 v64, v64
	v_exp_f32_e32 v65, v65
	v_and_b32_e32 v66, 0xffff0000, v215
	v_mul_f32_e32 v55, v55, v63
	v_add_f32_e32 v63, 1.0, v64
	v_add_f32_e32 v64, 1.0, v65
	v_lshlrev_b32_e32 v65, 16, v215
	v_mul_f32_e32 v66, 0xbfb8aa3b, v66
	v_mul_f32_e32 v65, 0xbfb8aa3b, v65
	v_exp_f32_e32 v66, v66
	v_exp_f32_e32 v70, v70
	v_exp_f32_e32 v65, v65
	v_rcp_f32_e32 v63, v63
	v_add_f32_e32 v66, 1.0, v66
	v_add_f32_e32 v70, 1.0, v70
	v_add_f32_e32 v65, 1.0, v65
	v_rcp_f32_e32 v66, v66
	v_rcp_f32_e32 v70, v70
	v_rcp_f32_e32 v64, v64
	v_rcp_f32_e32 v65, v65
	v_mul_f32_e32 v51, v51, v66
	v_mul_f32_e32 v54, v54, v70
	v_mul_f32_e32 v63, v48, v63
	v_mul_f32_e32 v64, v49, v64
	v_mul_f32_e32 v65, v50, v65
	v_cvt_pk_bf16_f32 v48, v52, v53
	v_cvt_pk_bf16_f32 v49, v54, v55
	v_cvt_pk_bf16_f32 v50, v63, v64
	v_cvt_pk_bf16_f32 v51, v65, v51
	global_store_dwordx4 v[60:61], v[48:51], off offset:256
	v_ashrrev_i32_e32 v63, 31, v62
	s_waitcnt vmcnt(15)
	v_lshlrev_b32_e32 v52, 16, v216
	v_and_b32_e32 v55, 0xffff0000, v216
	v_lshlrev_b32_e32 v56, 16, v217
	v_mul_f32_e32 v55, 0xbfb8aa3b, v55
	v_mul_f32_e32 v56, 0xbfb8aa3b, v56
	v_mul_f32_e32 v52, 0xbfb8aa3b, v52
	v_exp_f32_e32 v55, v55
	v_exp_f32_e32 v56, v56
	v_exp_f32_e32 v54, v52
	v_and_b32_e32 v57, 0xffff0000, v217
	v_add_f32_e32 v55, 1.0, v55
	v_add_f32_e32 v56, 1.0, v56
	v_add_f32_e32 v54, 1.0, v54
	v_rcp_f32_e32 v55, v55
	v_rcp_f32_e32 v56, v56
	v_mul_f32_e32 v57, 0xbfb8aa3b, v57
	v_rcp_f32_e32 v54, v54
	v_exp_f32_e32 v57, v57
	v_mul_f32_e32 v55, v45, v55
	v_mul_f32_e32 v46, v46, v56
	v_lshlrev_b32_e32 v45, 16, v218
	v_and_b32_e32 v56, 0xffff0000, v218
	v_mul_f32_e32 v54, v44, v54
	v_add_f32_e32 v44, 1.0, v57
	v_mul_f32_e32 v45, 0xbfb8aa3b, v45
	v_mul_f32_e32 v56, 0xbfb8aa3b, v56
	v_rcp_f32_e32 v44, v44
	v_exp_f32_e32 v45, v45
	v_exp_f32_e32 v56, v56
	v_and_b32_e32 v57, 0xffff0000, v219
	v_mul_f32_e32 v47, v47, v44
	v_add_f32_e32 v44, 1.0, v45
	v_add_f32_e32 v45, 1.0, v56
	v_lshlrev_b32_e32 v56, 16, v219
	v_mul_f32_e32 v57, 0xbfb8aa3b, v57
	v_mul_f32_e32 v56, 0xbfb8aa3b, v56
	v_exp_f32_e32 v57, v57
	v_exp_f32_e32 v56, v56
	v_rcp_f32_e32 v44, v44
	v_rcp_f32_e32 v45, v45
	v_add_f32_e32 v57, 1.0, v57
	v_add_f32_e32 v56, 1.0, v56
	v_rcp_f32_e32 v57, v57
	v_rcp_f32_e32 v56, v56
	v_lshlrev_b64 v[52:53], 12, v[62:63]
	v_mul_f32_e32 v58, v40, v44
	v_mul_f32_e32 v59, v41, v45
	v_lshl_add_u64 v[40:41], s[2:3], 0, v[52:53]
	v_mul_f32_e32 v43, v43, v57
	v_lshl_add_u64 v[44:45], v[40:41], 0, v[144:145]
	v_cvt_pk_bf16_f32 v40, v54, v55
	v_cvt_pk_bf16_f32 v41, v46, v47
	v_add_u32_e32 v46, 0xa0, v146
	v_mul_f32_e32 v56, v42, v56
	v_cvt_pk_bf16_f32 v42, v58, v59
	v_cvt_pk_bf16_f32 v43, v56, v43
	global_store_dwordx4 v[44:45], v[40:43], off
	s_waitcnt vmcnt(15)
	v_lshlrev_b32_e32 v47, 16, v220
	v_and_b32_e32 v48, 0xffff0000, v220
	v_mad_i64_i32 v[40:41], s[0:1], v46, s38, v[148:149]
	v_lshl_add_u64 v[52:53], v[40:41], 0, v[144:145]
	v_mul_f32_e32 v47, 0xbfb8aa3b, v47
	v_mul_f32_e32 v48, 0xbfb8aa3b, v48
	v_exp_f32_e32 v47, v47
	v_exp_f32_e32 v48, v48
	v_lshlrev_b32_e32 v54, 16, v221
	v_and_b32_e32 v49, 0xffff0000, v221
	v_add_f32_e32 v47, 1.0, v47
	v_add_f32_e32 v48, 1.0, v48
	v_mul_f32_e32 v49, 0xbfb8aa3b, v49
	v_rcp_f32_e32 v47, v47
	v_rcp_f32_e32 v48, v48
	v_exp_f32_e32 v49, v49
	v_mul_f32_e32 v54, 0xbfb8aa3b, v54
	v_mul_f32_e32 v36, v36, v47
	v_mul_f32_e32 v37, v37, v48
	v_add_f32_e32 v47, 1.0, v49
	v_lshlrev_b32_e32 v48, 16, v222
	v_and_b32_e32 v49, 0xffff0000, v222
	v_mul_f32_e32 v48, 0xbfb8aa3b, v48
	v_mul_f32_e32 v49, 0xbfb8aa3b, v49
	v_rcp_f32_e32 v47, v47
	v_exp_f32_e32 v48, v48
	v_exp_f32_e32 v49, v49
	v_and_b32_e32 v50, 0xffff0000, v223
	v_mul_f32_e32 v39, v39, v47
	v_add_f32_e32 v47, 1.0, v48
	v_add_f32_e32 v48, 1.0, v49
	v_lshlrev_b32_e32 v49, 16, v223
	v_mul_f32_e32 v50, 0xbfb8aa3b, v50
	v_mul_f32_e32 v49, 0xbfb8aa3b, v49
	v_exp_f32_e32 v50, v50
	v_exp_f32_e32 v54, v54
	v_exp_f32_e32 v49, v49
	v_rcp_f32_e32 v47, v47
	v_add_f32_e32 v50, 1.0, v50
	v_add_f32_e32 v54, 1.0, v54
	v_add_f32_e32 v49, 1.0, v49
	v_rcp_f32_e32 v50, v50
	v_rcp_f32_e32 v54, v54
	v_rcp_f32_e32 v48, v48
	v_rcp_f32_e32 v49, v49
	v_mul_f32_e32 v35, v35, v50
	v_mul_f32_e32 v38, v38, v54
	v_mul_f32_e32 v47, v32, v47
	v_mul_f32_e32 v48, v33, v48
	v_mul_f32_e32 v49, v34, v49
	v_cvt_pk_bf16_f32 v32, v36, v37
	v_cvt_pk_bf16_f32 v33, v38, v39
	v_cvt_pk_bf16_f32 v34, v47, v48
	v_cvt_pk_bf16_f32 v35, v49, v35
	global_store_dwordx4 v[44:45], v[32:35], off offset:256
	v_ashrrev_i32_e32 v47, 31, v46
	s_waitcnt vmcnt(15)
	v_lshlrev_b32_e32 v36, 16, v224
	v_and_b32_e32 v39, 0xffff0000, v224
	v_lshlrev_b32_e32 v40, 16, v225
	v_mul_f32_e32 v39, 0xbfb8aa3b, v39
	v_mul_f32_e32 v40, 0xbfb8aa3b, v40
	v_mul_f32_e32 v36, 0xbfb8aa3b, v36
	v_exp_f32_e32 v39, v39
	v_exp_f32_e32 v40, v40
	v_exp_f32_e32 v38, v36
	v_and_b32_e32 v41, 0xffff0000, v225
	v_add_f32_e32 v39, 1.0, v39
	v_add_f32_e32 v40, 1.0, v40
	v_add_f32_e32 v38, 1.0, v38
	v_rcp_f32_e32 v39, v39
	v_rcp_f32_e32 v40, v40
	v_mul_f32_e32 v41, 0xbfb8aa3b, v41
	v_rcp_f32_e32 v38, v38
	v_exp_f32_e32 v41, v41
	v_mul_f32_e32 v39, v29, v39
	v_mul_f32_e32 v30, v30, v40
	v_lshlrev_b32_e32 v29, 16, v226
	v_and_b32_e32 v40, 0xffff0000, v226
	v_mul_f32_e32 v38, v28, v38
	v_add_f32_e32 v28, 1.0, v41
	v_mul_f32_e32 v29, 0xbfb8aa3b, v29
	v_mul_f32_e32 v40, 0xbfb8aa3b, v40
	v_rcp_f32_e32 v28, v28
	v_exp_f32_e32 v29, v29
	v_exp_f32_e32 v40, v40
	v_and_b32_e32 v41, 0xffff0000, v227
	v_mul_f32_e32 v31, v31, v28
	v_add_f32_e32 v28, 1.0, v29
	v_add_f32_e32 v29, 1.0, v40
	v_lshlrev_b32_e32 v40, 16, v227
	v_mul_f32_e32 v41, 0xbfb8aa3b, v41
	v_mul_f32_e32 v40, 0xbfb8aa3b, v40
	v_exp_f32_e32 v41, v41
	v_exp_f32_e32 v40, v40
	v_rcp_f32_e32 v28, v28
	v_rcp_f32_e32 v29, v29
	v_add_f32_e32 v41, 1.0, v41
	v_add_f32_e32 v40, 1.0, v40
	v_rcp_f32_e32 v41, v41
	v_rcp_f32_e32 v40, v40
	v_lshlrev_b64 v[36:37], 12, v[46:47]
	v_mul_f32_e32 v42, v24, v28
	v_mul_f32_e32 v43, v25, v29
	v_lshl_add_u64 v[24:25], s[2:3], 0, v[36:37]
	v_mul_f32_e32 v27, v27, v41
	v_lshl_add_u64 v[28:29], v[24:25], 0, v[144:145]
	v_cvt_pk_bf16_f32 v24, v38, v39
	v_mul_f32_e32 v40, v26, v40
	v_cvt_pk_bf16_f32 v25, v30, v31
	v_cvt_pk_bf16_f32 v26, v42, v43
	v_cvt_pk_bf16_f32 v27, v40, v27
	global_store_dwordx4 v[28:29], v[24:27], off
	v_add_u32_e32 v30, 0xb0, v146
	s_waitcnt vmcnt(15)
	v_lshlrev_b32_e32 v38, 16, v229
	v_lshlrev_b32_e32 v24, 16, v228
	v_mul_f32_e32 v31, 0xbfb8aa3b, v24
	v_mad_i64_i32 v[24:25], s[0:1], v30, s38, v[148:149]
	v_lshl_add_u64 v[36:37], v[24:25], 0, v[144:145]
	v_and_b32_e32 v32, 0xffff0000, v228
	v_mul_f32_e32 v32, 0xbfb8aa3b, v32
	v_exp_f32_e32 v31, v31
	v_exp_f32_e32 v32, v32
	v_and_b32_e32 v33, 0xffff0000, v229
	v_mul_f32_e32 v33, 0xbfb8aa3b, v33
	v_add_f32_e32 v31, 1.0, v31
	v_add_f32_e32 v32, 1.0, v32
	v_rcp_f32_e32 v31, v31
	v_rcp_f32_e32 v32, v32
	v_exp_f32_e32 v33, v33
	v_mul_f32_e32 v38, 0xbfb8aa3b, v38
	v_mul_f32_e32 v20, v20, v31
	v_mul_f32_e32 v21, v21, v32
	v_add_f32_e32 v31, 1.0, v33
	v_lshlrev_b32_e32 v32, 16, v230
	v_and_b32_e32 v33, 0xffff0000, v230
	v_mul_f32_e32 v32, 0xbfb8aa3b, v32
	v_mul_f32_e32 v33, 0xbfb8aa3b, v33
	v_rcp_f32_e32 v31, v31
	v_exp_f32_e32 v32, v32
	v_exp_f32_e32 v33, v33
	v_and_b32_e32 v34, 0xffff0000, v231
	v_mul_f32_e32 v23, v23, v31
	v_add_f32_e32 v31, 1.0, v32
	v_add_f32_e32 v32, 1.0, v33
	v_lshlrev_b32_e32 v33, 16, v231
	v_mul_f32_e32 v34, 0xbfb8aa3b, v34
	v_mul_f32_e32 v33, 0xbfb8aa3b, v33
	v_exp_f32_e32 v34, v34
	v_exp_f32_e32 v38, v38
	v_exp_f32_e32 v33, v33
	v_rcp_f32_e32 v31, v31
	v_add_f32_e32 v34, 1.0, v34
	v_add_f32_e32 v38, 1.0, v38
	v_add_f32_e32 v33, 1.0, v33
	v_rcp_f32_e32 v34, v34
	v_rcp_f32_e32 v38, v38
	v_rcp_f32_e32 v32, v32
	v_rcp_f32_e32 v33, v33
	v_mul_f32_e32 v19, v19, v34
	v_mul_f32_e32 v22, v22, v38
	v_mul_f32_e32 v31, v16, v31
	v_mul_f32_e32 v32, v17, v32
	v_mul_f32_e32 v33, v18, v33
	v_cvt_pk_bf16_f32 v16, v20, v21
	v_cvt_pk_bf16_f32 v17, v22, v23
	v_cvt_pk_bf16_f32 v18, v31, v32
	v_cvt_pk_bf16_f32 v19, v33, v19
	global_store_dwordx4 v[28:29], v[16:19], off offset:256
	v_ashrrev_i32_e32 v31, 31, v30
	s_mov_b64 s[0:1], -1
	s_waitcnt vmcnt(15)
	v_lshlrev_b32_e32 v20, 16, v236
	v_and_b32_e32 v23, 0xffff0000, v236
	v_lshlrev_b32_e32 v24, 16, v237
	v_mul_f32_e32 v23, 0xbfb8aa3b, v23
	v_mul_f32_e32 v24, 0xbfb8aa3b, v24
	v_mul_f32_e32 v20, 0xbfb8aa3b, v20
	v_exp_f32_e32 v23, v23
	v_exp_f32_e32 v24, v24
	v_exp_f32_e32 v22, v20
	v_and_b32_e32 v25, 0xffff0000, v237
	v_add_f32_e32 v23, 1.0, v23
	v_add_f32_e32 v24, 1.0, v24
	v_add_f32_e32 v22, 1.0, v22
	v_rcp_f32_e32 v23, v23
	v_rcp_f32_e32 v24, v24
	v_mul_f32_e32 v25, 0xbfb8aa3b, v25
	v_rcp_f32_e32 v22, v22
	v_exp_f32_e32 v25, v25
	v_mul_f32_e32 v23, v13, v23
	v_mul_f32_e32 v14, v14, v24
	v_lshlrev_b32_e32 v13, 16, v238
	v_and_b32_e32 v24, 0xffff0000, v238
	v_mul_f32_e32 v22, v12, v22
	v_add_f32_e32 v12, 1.0, v25
	v_mul_f32_e32 v13, 0xbfb8aa3b, v13
	v_mul_f32_e32 v24, 0xbfb8aa3b, v24
	v_rcp_f32_e32 v12, v12
	v_exp_f32_e32 v13, v13
	v_exp_f32_e32 v24, v24
	v_and_b32_e32 v25, 0xffff0000, v239
	v_mul_f32_e32 v15, v15, v12
	v_add_f32_e32 v12, 1.0, v13
	v_add_f32_e32 v13, 1.0, v24
	v_lshlrev_b32_e32 v24, 16, v239
	v_mul_f32_e32 v24, 0xbfb8aa3b, v24
	v_exp_f32_e32 v24, v24
	v_mul_f32_e32 v25, 0xbfb8aa3b, v25
	v_exp_f32_e32 v25, v25
	v_rcp_f32_e32 v12, v12
	v_add_f32_e32 v24, 1.0, v24
	v_rcp_f32_e32 v24, v24
	v_rcp_f32_e32 v13, v13
	v_add_f32_e32 v25, 1.0, v25
	v_rcp_f32_e32 v25, v25
	v_lshlrev_b64 v[20:21], 12, v[30:31]
	v_mul_f32_e32 v24, v10, v24
	v_mul_f32_e32 v26, v8, v12
	v_mul_f32_e32 v27, v9, v13
	v_lshl_add_u64 v[8:9], s[2:3], 0, v[20:21]
	v_mul_f32_e32 v11, v11, v25
	s_waitcnt vmcnt(14)
	v_lshlrev_b32_e32 v10, 16, v240
	v_mul_f32_e32 v10, 0xbfb8aa3b, v10
	v_lshl_add_u64 v[12:13], v[8:9], 0, v[144:145]
	v_cvt_pk_bf16_f32 v9, v14, v15
	v_exp_f32_e32 v14, v10
	v_cvt_pk_bf16_f32 v10, v26, v27
	v_cvt_pk_bf16_f32 v8, v22, v23
	v_cvt_pk_bf16_f32 v11, v24, v11
	global_store_dwordx4 v[12:13], v[8:11], off
	s_nop 1
	v_and_b32_e32 v9, 0xffff0000, v240
	v_lshlrev_b32_e32 v10, 16, v241
	v_mul_f32_e32 v9, 0xbfb8aa3b, v9
	v_mul_f32_e32 v10, 0xbfb8aa3b, v10
	v_exp_f32_e32 v9, v9
	v_exp_f32_e32 v10, v10
	v_and_b32_e32 v11, 0xffff0000, v241
	v_add_f32_e32 v8, 1.0, v14
	v_add_f32_e32 v9, 1.0, v9
	v_add_f32_e32 v10, 1.0, v10
	v_rcp_f32_e32 v9, v9
	v_rcp_f32_e32 v10, v10
	v_mul_f32_e32 v11, 0xbfb8aa3b, v11
	v_rcp_f32_e32 v8, v8
	v_exp_f32_e32 v11, v11
	v_mul_f32_e32 v5, v5, v9
	v_mul_f32_e32 v6, v6, v10
	v_lshlrev_b32_e32 v9, 16, v242
	v_and_b32_e32 v10, 0xffff0000, v242
	v_mul_f32_e32 v4, v4, v8
	v_add_f32_e32 v8, 1.0, v11
	v_mul_f32_e32 v9, 0xbfb8aa3b, v9
	v_mul_f32_e32 v10, 0xbfb8aa3b, v10
	v_rcp_f32_e32 v8, v8
	v_exp_f32_e32 v9, v9
	v_exp_f32_e32 v10, v10
	v_and_b32_e32 v11, 0xffff0000, v243
	v_mul_f32_e32 v7, v7, v8
	v_add_f32_e32 v8, 1.0, v9
	v_add_f32_e32 v9, 1.0, v10
	v_lshlrev_b32_e32 v10, 16, v243
	v_mul_f32_e32 v11, 0xbfb8aa3b, v11
	v_mul_f32_e32 v10, 0xbfb8aa3b, v10
	v_exp_f32_e32 v11, v11
	v_exp_f32_e32 v10, v10
	v_rcp_f32_e32 v8, v8
	v_rcp_f32_e32 v9, v9
	v_add_f32_e32 v11, 1.0, v11
	v_add_f32_e32 v10, 1.0, v10
	v_rcp_f32_e32 v11, v11
	v_rcp_f32_e32 v10, v10
	v_mul_f32_e32 v8, v0, v8
	v_mul_f32_e32 v9, v1, v9
	v_mul_f32_e32 v3, v3, v11
	v_mul_f32_e32 v10, v2, v10
	v_cvt_pk_bf16_f32 v0, v4, v5
	v_cvt_pk_bf16_f32 v1, v6, v7
	v_cvt_pk_bf16_f32 v2, v8, v9
	v_cvt_pk_bf16_f32 v3, v10, v3
	global_store_dwordx4 v[12:13], v[0:3], off offset:256
	s_cbranch_vccnz .LBB0_832
	s_andn2_b64 vcc, exec, s[10:11]
	s_cbranch_vccnz .LBB0_831
	s_barrier
	s_branch .LBB0_831
